# MLA K prefetch: loop-invariant part of the row address folded into the per-lane base once per unit; per-chunk uniform offset by SALU, one 64-bit add per load
# speedup vs baseline: 1.0215x; 1.0073x over previous
; #define LAS __attribute__((address_space(3)))
; __device__ __forceinline__ int otid() { int t = threadIdx.x; asm volatile("" : "+v"(t)); return t; }
;   __device__ __forceinline__ bf16_t* PROJ() const { return (bf16_t*)(ws + WS_PROJ); }
;   __device__ __forceinline__ bf16_t* QM() const { return (bf16_t*)(ws + WS_QM); }
;   __device__ __forceinline__ bf16_t* KVM() const { return (bf16_t*)(ws + WS_KVM); }
; template <int NT, int DQK, int DV, int MODE, int PD, class Src> ...
;     ...
; #pragma unroll
;   for (int u = 0; u < PD; ++u) if (kc0 + u < kc1) ABL_LOAD(u, kc0 + u);
; __device__ __forceinline__ void mla_unit(LAS unsigned char* lds, const Ctx& X, int b, int h, int qb) {
;   const int tid = otid(), lane = tid & 63, w = __builtin_amdgcn_readfirstlane(tid >> 6), cq = lane & 15, lg = lane >> 4;
;   const size_t rowbase = (size_t)b * S; const int qw = qb * 256 + 32 * w;
;   bf16x8 qf[2][3]; int tq[2]; f32x4 o[2][4]; float m[2], l[2];
; #pragma unroll
;   for (int j = 0; j < 2; ++j) { tq[j] = qw + 16 * j + cq; m[j] = -INFINITY; l[j] = 0.f;
; #pragma unroll
;     for (int kk = 0; kk < 3; ++kk) qf[j][kk] = *(const bf16x8*)(X.QM() + (rowbase + tq[j]) * 768 + 96 * h + 32 * kk + 8 * lg);
; #pragma unroll
;     for (int dt = 0; dt < 4; ++dt) o[j][dt] = (f32x4){0.f, 0.f, 0.f, 0.f}; }
;   SrcMla src{X.KVM(), X.PROJ(), rowbase, h};
;   const float c = 0.10206207261596577f * LOG2E;
;   attn_block_loop<2, 96, 64, MODE_CAUSAL, 3, SrcMla>(lds, src, o, m, l, qf, tq, 0, 4 * (qb + 1), 0, qw, qw + 31, c, 0);
.LBB0_757:
	s_or_b64 exec, exec, s[18:19]
	v_and_b32_e32 v72, 63, v1
	v_lshlrev_b32_e32 v203, 4, v71
	v_and_b32_e32 v71, 15, v1
	v_add_u32_e32 v204, v67, v66
	v_mul_u32_u24_e32 v237, 0xd0, v71
	v_or_b32_e32 v71, 48, v72
	v_mul_lo_u32 v66, v204, 12
	v_add_u32_e32 v206, v70, v69
	s_and_b32 s8, s40, 7
	v_and_b32_e32 v236, 48, v1
	v_mul_u32_u24_e32 v238, 0xd0, v71
	v_bfe_u32 v71, v1, 2, 4
	v_lshlrev_b32_e32 v72, 3, v1
	v_sub_u32_e32 v1, v1, v66
	v_mul_lo_u32 v66, v206, 12
	s_lshl_b32 s40, s8, 8
	s_movk_i32 s8, 0xd0
	v_sub_u32_e32 v70, v68, v66
	v_lshlrev_b32_e32 v66, 3, v1
	v_mov_b32_e32 v67, v0
	v_ashrrev_i32_e32 v205, 31, v204
	v_mul_lo_u32 v242, v204, s8
	v_mul_lo_u32 v244, v206, s8
	v_ashrrev_i32_e32 v69, 31, v66
	v_mov_b32_e32 v68, v66
	v_lshl_add_u64 v[208:209], v[66:67], 1, s[38:39]
	s_lshl_b64 s[8:9], s[20:21], 24
	v_lshlrev_b64 v[66:67], 11, v[204:205]
	v_lshl_add_u64 v[66:67], s[8:9], 0, v[66:67]
	v_lshl_add_u64 v[66:67], v[68:69], 1, v[66:67]
	v_ashrrev_i32_e32 v207, 31, v206
	v_mul_lo_u32 v195, v62, s80
	v_lshlrev_b32_e32 v245, 4, v70
	v_cmp_lt_i32_e64 s[18:19], 7, v70
	v_lshlrev_b32_e32 v70, 3, v70
	v_lshl_add_u64 v[212:213], s[28:29], 0, v[66:67]
	v_lshlrev_b64 v[66:67], 11, v[206:207]
	v_lshlrev_b64 v[62:63], 11, v[62:63]
	v_and_b32_e32 v239, 24, v72
	v_ashrrev_i32_e32 v73, 31, v70
	v_mov_b32_e32 v72, v70
	v_lshl_add_u64 v[66:67], s[8:9], 0, v[66:67]
	v_lshl_add_u64 v[62:63], s[8:9], 0, v[62:63]
	v_mul_u32_u24_e32 v240, 0xa0, v71
	v_and_b32_e32 v241, 12, v71
	v_mov_b32_e32 v71, v0
	v_lshl_add_u64 v[66:67], v[72:73], 1, v[66:67]
	v_lshl_add_u64 v[62:63], v[64:65], 1, v[62:63]
	v_mov_b32_e32 v64, v0
	v_mov_b32_e32 v65, v0
	s_lshl_b32 s64, s52, 2
	v_lshlrev_b32_e32 v243, 4, v1
	v_cmp_lt_i32_e64 s[16:17], 7, v1
	v_lshl_add_u64 v[210:211], v[70:71], 1, s[38:39]
	v_lshl_add_u64 v[214:215], s[28:29], 0, v[66:67]
	v_lshl_add_u64 v[216:217], s[28:29], 0, v[62:63]
	v_mov_b32_e32 v1, v0
	v_mov_b32_e32 v201, v200
	v_mov_b32_e32 v62, v0
	v_mov_b32_e32 v63, v0
	v_mov_b64_e32 v[72:73], v[64:65]
	v_mov_b64_e32 v[80:81], v[64:65]
	v_mov_b64_e32 v[84:85], v[64:65]
	v_mov_b64_e32 v[68:69], v[64:65]
	v_mov_b64_e32 v[76:77], v[64:65]
	v_mov_b64_e32 v[88:89], v[64:65]
	v_mov_b64_e32 v[92:93], v[64:65]
	s_add_i32 s65, s64, 4
	s_or_b32 s68, s59, 31
	s_mov_b32 s72, 0
	s_movk_i32 s69, 0xbf
	v_mov_b64_e32 v[70:71], v[62:63]
	v_mov_b64_e32 v[78:79], v[62:63]
	v_mov_b64_e32 v[82:83], v[62:63]
	v_mov_b64_e32 v[66:67], v[62:63]
	v_mov_b64_e32 v[74:75], v[62:63]
	v_mov_b64_e32 v[86:87], v[62:63]
	v_mov_b64_e32 v[90:91], v[62:63]
	v_mov_b64_e32 v[220:221], v[200:201]
	v_mov_b64_e32 v[218:219], v[0:1]
	v_mov_b32_e32 v188, v204
	v_ashrrev_i32_e32 v189, 31, v204
	v_lshl_add_u64 v[188:189], s[46:47], 0, v[188:189]
	v_mad_u64_u32 v[208:209], s[100:101], v188, s82, v[208:209]
	v_mad_i32_i24 v209, v189, s82, v209
	v_lshl_add_u64 v[208:209], v[208:209], 0, s[96:97]
	v_mov_b32_e32 v188, v206
	v_ashrrev_i32_e32 v189, 31, v206
	v_lshl_add_u64 v[188:189], s[46:47], 0, v[188:189]
	v_mad_u64_u32 v[210:211], s[100:101], v188, s82, v[210:211]
	v_mad_i32_i24 v211, v189, s82, v211
	v_lshl_add_u64 v[210:211], v[210:211], 0, s[96:97]

; #define LAS __attribute__((address_space(3)))
; template <int NT, int DQK, int DV, int MODE, int PD, class Src> ...
;     ...
;   for (int kcb = kc0; kcb < kc1; kcb += PD) {
; #pragma unroll
;     for (int u = 0; u < PD; ++u) {
;       const int kc = kcb + u;
;       if (kc < kc1) {
;         LAS unsigned char* buf = lds + ((kc - kc0) & 1) * BUF;
; #pragma unroll
;         for (int rr = 0; rr < NKR; ++rr) { const int idx = tid + 512 * rr; if (idx < NKI) { const int row = idx / KCH, ch = idx % KCH; *(LAS u32x4*)(buf + row * KSTR + ch * 16) = kreg[u][rr]; } }
; #pragma unroll
;         for (int rr = 0; rr < NVR; ++rr) { const int idx = tid + 512 * rr; if (idx < NVI) { const int row = idx / VCH, ch = idx % VCH; *(LAS u32x4*)(buf + KB + row * VSTR + ch * 16) = vreg[u][rr]; } }
;         if (kc + PD < kc1) ABL_LOAD(u, kc + PD);
.LBB0_762:
	s_or_b64 exec, exec, s[20:21]
	s_add_i32 s70, s72, 3
	s_cmp_ge_u32 s70, s65
	s_cselect_b64 s[52:53], -1, 0
	s_cmp_lt_u32 s70, s65
	s_cbranch_scc0 .LBB0_768
	s_lshl_b32 s8, s70, 6
	s_mul_hi_u32 s101, s8, s82
	s_mul_i32 s100, s8, s82
	s_and_saveexec_b64 s[20:21], s[10:11]
	s_cbranch_execnz .LBB0_776
	s_or_b64 exec, exec, s[20:21]
	s_and_saveexec_b64 s[20:21], s[12:13]
	s_cbranch_execnz .LBB0_781

.LBB0_776:
	s_and_saveexec_b64 s[22:23], s[16:17]
	s_xor_b64 s[22:23], exec, s[22:23]
	s_cbranch_execz .LBB0_778
	v_lshl_add_u64 v[26:27], v[208:209], 0, s[100:101]

.LBB0_781:
	s_and_saveexec_b64 s[22:23], s[18:19]
	s_xor_b64 s[22:23], exec, s[22:23]
	s_cbranch_execz .LBB0_783
	v_lshl_add_u64 v[30:31], v[210:211], 0, s[100:101]

; #define LAS __attribute__((address_space(3)))
; template <int NT, int DQK, int DV, int MODE, int PD, class Src> ...
;     ...
;   for (int kcb = kc0; kcb < kc1; kcb += PD) {
; #pragma unroll
;     for (int u = 0; u < PD; ++u) {
;       const int kc = kcb + u;
;       if (kc < kc1) {
;         LAS unsigned char* buf = lds + ((kc - kc0) & 1) * BUF;
; #pragma unroll
;         for (int rr = 0; rr < NKR; ++rr) { const int idx = tid + 512 * rr; if (idx < NKI) { const int row = idx / KCH, ch = idx % KCH; *(LAS u32x4*)(buf + row * KSTR + ch * 16) = kreg[u][rr]; } }
; #pragma unroll
;         for (int rr = 0; rr < NVR; ++rr) { const int idx = tid + 512 * rr; if (idx < NVI) { const int row = idx / VCH, ch = idx % VCH; *(LAS u32x4*)(buf + KB + row * VSTR + ch * 16) = vreg[u][rr]; } }
;         if (kc + PD < kc1) ABL_LOAD(u, kc + PD);
.LBB0_805:
	s_lshl_b32 s8, s72, 6
	s_addk_i32 s8, 0x100
	s_mul_hi_u32 s101, s8, s82
	s_mul_i32 s100, s8, s82
	s_and_saveexec_b64 s[20:21], s[10:11]
	s_cbranch_execnz .LBB0_816
	s_or_b64 exec, exec, s[20:21]
	s_and_saveexec_b64 s[20:21], s[12:13]
	s_cbranch_execnz .LBB0_821

.LBB0_816:
	s_and_saveexec_b64 s[22:23], s[16:17]
	s_xor_b64 s[22:23], exec, s[22:23]
	s_cbranch_execz .LBB0_818
	v_lshl_add_u64 v[38:39], v[208:209], 0, s[100:101]

.LBB0_821:
	s_and_saveexec_b64 s[22:23], s[18:19]
	s_xor_b64 s[22:23], exec, s[22:23]
	s_cbranch_execz .LBB0_823
	v_lshl_add_u64 v[46:47], v[210:211], 0, s[100:101]

; #define LAS __attribute__((address_space(3)))
; template <int NT, int DQK, int DV, int MODE, int PD, class Src> ...
;     ...
;   for (int kcb = kc0; kcb < kc1; kcb += PD) {
; #pragma unroll
;     for (int u = 0; u < PD; ++u) {
;       const int kc = kcb + u;
;       if (kc < kc1) {
;         LAS unsigned char* buf = lds + ((kc - kc0) & 1) * BUF;
; #pragma unroll
;         for (int rr = 0; rr < NKR; ++rr) { const int idx = tid + 512 * rr; if (idx < NKI) { const int row = idx / KCH, ch = idx % KCH; *(LAS u32x4*)(buf + row * KSTR + ch * 16) = kreg[u][rr]; } }
; #pragma unroll
;         for (int rr = 0; rr < NVR; ++rr) { const int idx = tid + 512 * rr; if (idx < NVI) { const int row = idx / VCH, ch = idx % VCH; *(LAS u32x4*)(buf + KB + row * VSTR + ch * 16) = vreg[u][rr]; } }
;         if (kc + PD < kc1) ABL_LOAD(u, kc + PD);
.LBB0_845:
	s_lshl_b32 s8, s72, 6
	s_mul_hi_u32 s101, s8, s82
	s_mul_i32 s100, s8, s82
	s_and_saveexec_b64 s[20:21], s[10:11]
	s_cbranch_execnz .LBB0_856
	s_or_b64 exec, exec, s[20:21]
	s_and_saveexec_b64 s[20:21], s[12:13]
	s_cbranch_execnz .LBB0_861

.LBB0_856:
	s_and_saveexec_b64 s[22:23], s[16:17]
	s_xor_b64 s[22:23], exec, s[22:23]
	s_cbranch_execz .LBB0_858
	v_lshl_add_u64 v[50:51], v[208:209], 0, s[100:101]

.LBB0_861:
	s_and_saveexec_b64 s[22:23], s[18:19]
	s_xor_b64 s[22:23], exec, s[22:23]
	s_cbranch_execz .LBB0_863
	v_lshl_add_u64 v[58:59], v[210:211], 0, s[100:101]

; #define LAS __attribute__((address_space(3)))
; __device__ __forceinline__ int otid() { int t = threadIdx.x; asm volatile("" : "+v"(t)); return t; }
;   __device__ __forceinline__ bf16_t* PROJ() const { return (bf16_t*)(ws + WS_PROJ); }
;   __device__ __forceinline__ bf16_t* QM() const { return (bf16_t*)(ws + WS_QM); }
;   __device__ __forceinline__ bf16_t* KVM() const { return (bf16_t*)(ws + WS_KVM); }
; template <int NT, int DQK, int DV, int MODE, int PD, class Src> ...
;     ...
; #pragma unroll
;   for (int u = 0; u < PD; ++u) if (kc0 + u < kc1) ABL_LOAD(u, kc0 + u);
; __device__ __forceinline__ void mla_unit(LAS unsigned char* lds, const Ctx& X, int b, int h, int qb) {
;   const int tid = otid(), lane = tid & 63, w = __builtin_amdgcn_readfirstlane(tid >> 6), cq = lane & 15, lg = lane >> 4;
;   const size_t rowbase = (size_t)b * S; const int qw = qb * 256 + 32 * w;
;   bf16x8 qf[2][3]; int tq[2]; f32x4 o[2][4]; float m[2], l[2];
; #pragma unroll
;   for (int j = 0; j < 2; ++j) { tq[j] = qw + 16 * j + cq; m[j] = -INFINITY; l[j] = 0.f;
; #pragma unroll
;     for (int kk = 0; kk < 3; ++kk) qf[j][kk] = *(const bf16x8*)(X.QM() + (rowbase + tq[j]) * 768 + 96 * h + 32 * kk + 8 * lg);
; #pragma unroll
;     for (int dt = 0; dt < 4; ++dt) o[j][dt] = (f32x4){0.f, 0.f, 0.f, 0.f}; }
;   SrcMla src{X.KVM(), X.PROJ(), rowbase, h};
;   const float c = 0.10206207261596577f * LOG2E;
;   attn_block_loop<2, 96, 64, MODE_CAUSAL, 3, SrcMla>(lds, src, o, m, l, qf, tq, 0, 4 * (qb + 1), 0, qw, qw + 31, c, 0);
.LBB0_930:
	s_or_b64 exec, exec, s[16:17]
	v_and_b32_e32 v72, 63, v1
	v_lshlrev_b32_e32 v203, 4, v71
	v_and_b32_e32 v71, 15, v1
	v_add_u32_e32 v204, v67, v66
	v_mul_u32_u24_e32 v237, 0xd0, v71
	v_or_b32_e32 v71, 48, v72
	v_mul_lo_u32 v66, v204, 12
	v_add_u32_e32 v206, v70, v69
	v_and_b32_e32 v236, 48, v1
	v_mul_u32_u24_e32 v238, 0xd0, v71
	v_bfe_u32 v71, v1, 2, 4
	v_lshlrev_b32_e32 v72, 3, v1
	v_sub_u32_e32 v1, v1, v66
	v_mul_lo_u32 v66, v206, 12
	v_sub_u32_e32 v70, v68, v66
	v_lshlrev_b32_e32 v66, 3, v1
	v_mov_b32_e32 v67, v0
	v_ashrrev_i32_e32 v205, 31, v204
	v_ashrrev_i32_e32 v69, 31, v66
	v_mov_b32_e32 v68, v66
	v_lshl_add_u64 v[208:209], v[66:67], 1, s[46:47]
	v_lshlrev_b64 v[66:67], 11, v[204:205]
	v_lshlrev_b32_e32 v245, 4, v70
	v_cmp_lt_i32_e64 s[18:19], 7, v70
	v_lshlrev_b32_e32 v70, 3, v70
	v_lshl_add_u64 v[66:67], v[68:69], 1, v[66:67]
	v_ashrrev_i32_e32 v207, 31, v206
	v_mul_lo_u32 v195, v62, s80
	v_and_b32_e32 v239, 24, v72
	v_ashrrev_i32_e32 v73, 31, v70
	v_mov_b32_e32 v72, v70
	v_lshl_add_u64 v[212:213], s[26:27], 0, v[66:67]
	v_lshlrev_b64 v[66:67], 11, v[206:207]
	v_lshlrev_b64 v[62:63], 11, v[62:63]
	v_mul_u32_u24_e32 v240, 0xa0, v71
	v_and_b32_e32 v241, 12, v71
	v_mov_b32_e32 v71, v0
	v_lshl_add_u64 v[66:67], v[72:73], 1, v[66:67]
	v_lshl_add_u64 v[62:63], v[64:65], 1, v[62:63]
	v_mov_b32_e32 v64, v0
	v_mov_b32_e32 v65, v0
	s_lshl_b32 s34, s20, 2
	s_movk_i32 s8, 0xd0
	v_lshlrev_b32_e32 v243, 4, v1
	v_cmp_lt_i32_e64 s[16:17], 7, v1
	v_lshl_add_u64 v[210:211], v[70:71], 1, s[46:47]
	v_lshl_add_u64 v[214:215], s[26:27], 0, v[66:67]
	v_lshl_add_u64 v[216:217], s[26:27], 0, v[62:63]
	v_mov_b32_e32 v1, v0
	v_mov_b32_e32 v201, v200
	v_mov_b32_e32 v62, v0
	v_mov_b32_e32 v63, v0
	v_mov_b64_e32 v[72:73], v[64:65]
	v_mov_b64_e32 v[80:81], v[64:65]
	v_mov_b64_e32 v[84:85], v[64:65]
	v_mov_b64_e32 v[68:69], v[64:65]
	v_mov_b64_e32 v[76:77], v[64:65]
	v_mov_b64_e32 v[88:89], v[64:65]
	v_mov_b64_e32 v[92:93], v[64:65]
	s_add_i32 s35, s34, 4
	s_or_b32 s40, s25, 31
	v_mul_lo_u32 v242, v204, s8
	v_mul_lo_u32 v244, v206, s8
	s_mov_b32 s58, 0
	s_movk_i32 s43, 0xbf
	v_mov_b64_e32 v[70:71], v[62:63]
	v_mov_b64_e32 v[78:79], v[62:63]
	v_mov_b64_e32 v[82:83], v[62:63]
	v_mov_b64_e32 v[66:67], v[62:63]
	v_mov_b64_e32 v[74:75], v[62:63]
	v_mov_b64_e32 v[86:87], v[62:63]
	v_mov_b64_e32 v[90:91], v[62:63]
	v_mov_b64_e32 v[220:221], v[200:201]
	v_mov_b64_e32 v[218:219], v[0:1]
	v_mov_b32_e32 v188, v204
	v_ashrrev_i32_e32 v189, 31, v204
	v_lshl_add_u64 v[188:189], s[56:57], 0, v[188:189]
	v_mad_u64_u32 v[208:209], s[100:101], v188, s82, v[208:209]
	v_mad_i32_i24 v209, v189, s82, v209
	v_lshl_add_u64 v[208:209], v[208:209], 0, s[96:97]
	v_mov_b32_e32 v188, v206
	v_ashrrev_i32_e32 v189, 31, v206
	v_lshl_add_u64 v[188:189], s[56:57], 0, v[188:189]
	v_mad_u64_u32 v[210:211], s[100:101], v188, s82, v[210:211]
	v_mad_i32_i24 v211, v189, s82, v211
	v_lshl_add_u64 v[210:211], v[210:211], 0, s[96:97]

; #define LAS __attribute__((address_space(3)))
; template <int NT, int DQK, int DV, int MODE, int PD, class Src> ...
;     ...
;   for (int kcb = kc0; kcb < kc1; kcb += PD) {
; #pragma unroll
;     for (int u = 0; u < PD; ++u) {
;       const int kc = kcb + u;
;       if (kc < kc1) {
;         LAS unsigned char* buf = lds + ((kc - kc0) & 1) * BUF;
; #pragma unroll
;         for (int rr = 0; rr < NKR; ++rr) { const int idx = tid + 512 * rr; if (idx < NKI) { const int row = idx / KCH, ch = idx % KCH; *(LAS u32x4*)(buf + row * KSTR + ch * 16) = kreg[u][rr]; } }
; #pragma unroll
;         for (int rr = 0; rr < NVR; ++rr) { const int idx = tid + 512 * rr; if (idx < NVI) { const int row = idx / VCH, ch = idx % VCH; *(LAS u32x4*)(buf + KB + row * VSTR + ch * 16) = vreg[u][rr]; } }
;         if (kc + PD < kc1) ABL_LOAD(u, kc + PD);
.LBB0_935:
	s_or_b64 exec, exec, s[20:21]
	s_add_i32 s44, s58, 3
	s_cmp_ge_u32 s44, s35
	s_cselect_b64 s[64:65], -1, 0
	s_cmp_lt_u32 s44, s35
	s_cbranch_scc0 .LBB0_941
	s_lshl_b32 s8, s44, 6
	s_mul_hi_u32 s101, s8, s82
	s_mul_i32 s100, s8, s82
	s_and_saveexec_b64 s[20:21], s[10:11]
	s_cbranch_execnz .LBB0_949
	s_or_b64 exec, exec, s[20:21]
	s_and_saveexec_b64 s[20:21], s[12:13]
	s_cbranch_execnz .LBB0_954

; #define LAS __attribute__((address_space(3)))
; template <int NT, int DQK, int DV, int MODE, int PD, class Src> ...
;     ...
;   for (int kcb = kc0; kcb < kc1; kcb += PD) {
; #pragma unroll
;     for (int u = 0; u < PD; ++u) {
;       const int kc = kcb + u;
;       if (kc < kc1) {
;         LAS unsigned char* buf = lds + ((kc - kc0) & 1) * BUF;
; #pragma unroll
;         for (int rr = 0; rr < NKR; ++rr) { const int idx = tid + 512 * rr; if (idx < NKI) { const int row = idx / KCH, ch = idx % KCH; *(LAS u32x4*)(buf + row * KSTR + ch * 16) = kreg[u][rr]; } }
; #pragma unroll
;         for (int rr = 0; rr < NVR; ++rr) { const int idx = tid + 512 * rr; if (idx < NVI) { const int row = idx / VCH, ch = idx % VCH; *(LAS u32x4*)(buf + KB + row * VSTR + ch * 16) = vreg[u][rr]; } }
;         if (kc + PD < kc1) ABL_LOAD(u, kc + PD);
.LBB0_978:
	s_lshl_b32 s8, s58, 6
	s_addk_i32 s8, 0x100
	s_mul_hi_u32 s101, s8, s82
	s_mul_i32 s100, s8, s82
	s_and_saveexec_b64 s[20:21], s[10:11]
	s_cbranch_execnz .LBB0_989
	s_or_b64 exec, exec, s[20:21]
	s_and_saveexec_b64 s[20:21], s[12:13]
	s_cbranch_execnz .LBB0_994

; #define LAS __attribute__((address_space(3)))
; template <int NT, int DQK, int DV, int MODE, int PD, class Src> ...
;     ...
;   for (int kcb = kc0; kcb < kc1; kcb += PD) {
; #pragma unroll
;     for (int u = 0; u < PD; ++u) {
;       const int kc = kcb + u;
;       if (kc < kc1) {
;         LAS unsigned char* buf = lds + ((kc - kc0) & 1) * BUF;
; #pragma unroll
;         for (int rr = 0; rr < NKR; ++rr) { const int idx = tid + 512 * rr; if (idx < NKI) { const int row = idx / KCH, ch = idx % KCH; *(LAS u32x4*)(buf + row * KSTR + ch * 16) = kreg[u][rr]; } }
; #pragma unroll
;         for (int rr = 0; rr < NVR; ++rr) { const int idx = tid + 512 * rr; if (idx < NVI) { const int row = idx / VCH, ch = idx % VCH; *(LAS u32x4*)(buf + KB + row * VSTR + ch * 16) = vreg[u][rr]; } }
;         if (kc + PD < kc1) ABL_LOAD(u, kc + PD);
.LBB0_1018:
	s_lshl_b32 s8, s58, 6
	s_mul_hi_u32 s101, s8, s82
	s_mul_i32 s100, s8, s82
	s_and_saveexec_b64 s[20:21], s[10:11]
	s_cbranch_execnz .LBB0_1029
	s_or_b64 exec, exec, s[20:21]
	s_and_saveexec_b64 s[20:21], s[12:13]
	s_cbranch_execnz .LBB0_1034

; #define LAS __attribute__((address_space(3)))
; __global__ void __launch_bounds__(512, 2) mega(Params P) {
;   extern __shared__ __attribute__((aligned(16))) unsigned char lds_raw[];
;   LAS unsigned char* lds = (LAS unsigned char*)lds_raw;
;   cg::grid_group grid = cg::this_grid();
;   if (threadIdx.x < 16) ((LAS unsigned*)(lds + (LDS_BYTES - 64)))[threadIdx.x] = 0u;
;   __syncthreads();
;   (void)xcd_barrier_post((unsigned*)(P.ws + WS_BAR), (volatile LAS unsigned*)(lds + (LDS_BYTES - 64)));
	.amdhsa_kernel _Z4mega6Params
		.amdhsa_group_segment_fixed_size 0
		.amdhsa_private_segment_fixed_size 0
		.amdhsa_kernarg_size 704
		.amdhsa_user_sgpr_count 2
		.amdhsa_user_sgpr_dispatch_ptr 0
		.amdhsa_user_sgpr_queue_ptr 0
		.amdhsa_user_sgpr_kernarg_segment_ptr 1
		.amdhsa_user_sgpr_dispatch_id 0
		.amdhsa_user_sgpr_kernarg_preload_length 0
		.amdhsa_user_sgpr_kernarg_preload_offset 0
		.amdhsa_user_sgpr_private_segment_size 0
		.amdhsa_uses_dynamic_stack 0
		.amdhsa_enable_private_segment 0
		.amdhsa_system_sgpr_workgroup_id_x 1
		.amdhsa_system_sgpr_workgroup_id_y 0
		.amdhsa_system_sgpr_workgroup_id_z 0
		.amdhsa_system_sgpr_workgroup_info 0
		.amdhsa_system_vgpr_workitem_id 2
		.amdhsa_next_free_vgpr 256
		.amdhsa_next_free_sgpr 102
		.amdhsa_accum_offset 256
		.amdhsa_reserve_vcc 1
		.amdhsa_float_round_mode_32 0
		.amdhsa_float_round_mode_16_64 0
		.amdhsa_float_denorm_mode_32 3
		.amdhsa_float_denorm_mode_16_64 3
		.amdhsa_dx10_clamp 1
		.amdhsa_ieee_mode 1
		.amdhsa_fp16_overflow 0
		.amdhsa_tg_split 0
		.amdhsa_exception_fp_ieee_invalid_op 0
		.amdhsa_exception_fp_denorm_src 0
		.amdhsa_exception_fp_ieee_div_zero 0
		.amdhsa_exception_fp_ieee_overflow 0
		.amdhsa_exception_fp_ieee_underflow 0
		.amdhsa_exception_fp_ieee_inexact 0
		.amdhsa_exception_int_div_zero 0
	.end_amdhsa_kernel

; #define LAS __attribute__((address_space(3)))
; __global__ void __launch_bounds__(512, 2) mega(Params P) {
;   extern __shared__ __attribute__((aligned(16))) unsigned char lds_raw[];
;   LAS unsigned char* lds = (LAS unsigned char*)lds_raw;
amdhsa.kernels:
  - .agpr_count:     0
    .args:
      - .offset:         0
        .size:           448
        .value_kind:     by_value
      - .offset:         448
        .size:           4
        .value_kind:     hidden_block_count_x
      - .offset:         452
        .size:           4
        .value_kind:     hidden_block_count_y
      - .offset:         456
        .size:           4
        .value_kind:     hidden_block_count_z
      - .offset:         460
        .size:           2
        .value_kind:     hidden_group_size_x
      - .offset:         462
        .size:           2
        .value_kind:     hidden_group_size_y
      - .offset:         464
        .size:           2
        .value_kind:     hidden_group_size_z
      - .offset:         466
        .size:           2
        .value_kind:     hidden_remainder_x
      - .offset:         468
        .size:           2
        .value_kind:     hidden_remainder_y
      - .offset:         470
        .size:           2
        .value_kind:     hidden_remainder_z
      - .offset:         488
        .size:           8
        .value_kind:     hidden_global_offset_x
      - .offset:         496
        .size:           8
        .value_kind:     hidden_global_offset_y
      - .offset:         504
        .size:           8
        .value_kind:     hidden_global_offset_z
      - .offset:         512
        .size:           2
        .value_kind:     hidden_grid_dims
      - .offset:         536
        .size:           8
        .value_kind:     hidden_multigrid_sync_arg
      - .offset:         568
        .size:           4
        .value_kind:     hidden_dynamic_lds_size
    .group_segment_fixed_size: 0
    .kernarg_segment_align: 8
    .kernarg_segment_size: 704
    .language:       OpenCL C
    .language_version:
      - 2
      - 0
    .max_flat_workgroup_size: 512
    .name:           _Z4mega6Params
    .private_segment_fixed_size: 0
    .sgpr_count:     108
    .sgpr_spill_count: 137
    .symbol:         _Z4mega6Params.kd
    .uniform_work_group_size: 1
    .uses_dynamic_stack: false
    .vgpr_count:     256
    .vgpr_spill_count: 0
    .wavefront_size: 64
